# up-proj epilogue: hoist 8 row-scale loads, single wait, stores stream
# speedup vs baseline: 1.0012x; 1.0012x over previous
; __device__ __forceinline__ u32x4 pack8(const f32x4& a, const f32x4& b) { u32x4 w; w.x = cvt_pk_bf16(a[0], a[1]); w.y = cvt_pk_bf16(a[2], a[3]); w.z = cvt_pk_bf16(b[0], b[1]); w.w = cvt_pk_bf16(b[2], b[3]); return w; }
;     __device__ __forceinline__ void operator()(const f32x4 (&acc)[2][2][4][2], const Unit& u, int wr, int wc, int fr, int fq) const {
;         const int row0 = u.pm * BM + wr * 64 + fr; const unsigned base = epi_img_base(u.pm, u.pn, wr, wc, fr, fq, Kact); const unsigned kb = (unsigned)(Kact >> 5) * 512u;
; #pragma unroll
;         for (int ai = 0; ai < 2; ++ai)
; #pragma unroll
;             for (int m = 0; m < 4; ++m) { const float r2 = 1.f / ((float)ss[row0 + ai * HALF + m * 16] * (SS_INV / DM) + 1e-6f);
; #pragma unroll
;                 for (int bj = 0; bj < 2; ++bj) { f32x4 v0 = acc[ai][bj][m][0], v1 = acc[ai][bj][m][1];
;                     v0 = __builtin_elementwise_max(v0, (f32x4){0.f, 0.f, 0.f, 0.f}); v1 = __builtin_elementwise_max(v1, (f32x4){0.f, 0.f, 0.f, 0.f}); v0 = v0 * v0 * r2; v1 = v1 * v1 * r2;
;                     *(u32x4*)(O + (size_t)(base + (unsigned)(8 * ai + m) * kb + (unsigned)(4 * bj) * 512u)) = pack8(v0, v1); } }
.LBB0_681:
	v_lshl_add_u32 v138, s22, 8, v142
	v_ashrrev_i32_e32 v139, 31, v138
	v_lshl_add_u64 v[138:139], v[138:139], 3, s[10:11]
	global_load_dwordx2 v[160:161], v[138:139], off
	global_load_dwordx2 v[162:163], v[138:139], off offset:128
	global_load_dwordx2 v[164:165], v[138:139], off offset:256
	global_load_dwordx2 v[166:167], v[138:139], off offset:384
	global_load_dwordx2 v[168:169], v[138:139], off offset:1024
	global_load_dwordx2 v[170:171], v[138:139], off offset:1152
	global_load_dwordx2 v[172:173], v[138:139], off offset:1280
	global_load_dwordx2 v[174:175], v[138:139], off offset:1408
	v_max_f32_e32 v125, v125, v125
	v_max_f32_e32 v146, v121, v121
	v_max_f32_e32 v114, v114, v114
	v_max_f32_e32 v127, v127, v127
	v_max_f32_e32 v148, v119, v119
	v_max_f32_e32 v121, 0, v125
	v_max_f32_e32 v125, 0, v146
	v_max_f32_e32 v146, 0, v114
	v_max_f32_e32 v119, 0, v127
	v_max_f32_e32 v127, 0, v148
	v_max_f32_e32 v126, v126, v126
	v_max_f32_e32 v149, v118, v118
	v_max_f32_e32 v118, 0, v126
	v_max_f32_e32 v126, 0, v149
	s_lshl_b32 s0, s0, 12
	s_lshl_b32 s1, s22, 22
	v_max_f32_e32 v129, v129, v129
	v_max_f32_e32 v150, v117, v117
	s_add_i32 s0, s0, s45
	v_max_f32_e32 v128, v128, v128
	v_max_f32_e32 v151, v116, v116
	v_max_f32_e32 v117, 0, v129
	v_max_f32_e32 v129, 0, v150
	s_add_i32 s1, s1, s0
	v_max_f32_e32 v124, v124, v124
	v_max_f32_e32 v147, v120, v120
	v_max_f32_e32 v152, v115, v115
	v_max_f32_e32 v116, 0, v128
	v_max_f32_e32 v128, 0, v151
	v_or_b32_e32 v178, s1, v144
	v_max_f32_e32 v120, 0, v124
	v_max_f32_e32 v124, 0, v147
	v_max_f32_e32 v147, 0, v152
	v_mov_b32_e32 v115, v179
	v_max_f32_e32 v123, v123, v123
	v_max_f32_e32 v122, v122, v122
	v_max_f32_e32 v123, 0, v123
	v_max_f32_e32 v122, 0, v122
	v_pk_mul_f32 v[118:119], v[118:119], v[118:119]
	v_pk_mul_f32 v[116:117], v[116:117], v[116:117]
	v_pk_mul_f32 v[122:123], v[122:123], v[122:123]
	v_pk_mul_f32 v[120:121], v[120:121], v[120:121]
	v_pk_mul_f32 v[126:127], v[126:127], v[126:127]
	v_pk_mul_f32 v[124:125], v[124:125], v[124:125]
	v_pk_mul_f32 v[146:147], v[146:147], v[146:147]
	v_pk_mul_f32 v[128:129], v[128:129], v[128:129]
	v_max_f32_e32 v110, v110, v110
	v_max_f32_e32 v98, v98, v98
	v_max_f32_e32 v112, v112, v112
	v_max_f32_e32 v111, v111, v111
	v_max_f32_e32 v109, v109, v109
	v_max_f32_e32 v113, v113, v113
	v_max_f32_e32 v108, v108, v108
	v_max_f32_e32 v106, v106, v106
	v_max_f32_e32 v94, v94, v94
	v_max_f32_e32 v82, v82, v82
	v_max_f32_e32 v96, v96, v96
	v_max_f32_e32 v95, v95, v95
	v_max_f32_e32 v93, v93, v93
	v_max_f32_e32 v97, v97, v97
	v_max_f32_e32 v92, v92, v92
	v_max_f32_e32 v90, v90, v90
	v_max_f32_e32 v78, v78, v78
	v_max_f32_e32 v66, v66, v66
	v_max_f32_e32 v80, v80, v80
	v_max_f32_e32 v79, v79, v79
	v_max_f32_e32 v77, v77, v77
	v_max_f32_e32 v81, v81, v81
	v_max_f32_e32 v76, v76, v76
	v_max_f32_e32 v74, v74, v74
	v_max_f32_e32 v62, v62, v62
	v_max_f32_e32 v50, v50, v50
	v_max_f32_e32 v64, v64, v64
	v_max_f32_e32 v63, v63, v63
	v_max_f32_e32 v61, v61, v61
	v_max_f32_e32 v65, v65, v65
	v_max_f32_e32 v60, v60, v60
	v_max_f32_e32 v58, v58, v58
	v_max_f32_e32 v46, v46, v46
	s_waitcnt vmcnt(0)
	v_mov_b32_e32 v140, v160
	v_mov_b32_e32 v141, v161
	v_ffbh_u32_e32 v114, v141
	v_min_u32_e32 v148, 32, v114
	v_lshlrev_b64 v[140:141], v148, v[140:141]
	v_min_u32_e32 v114, 1, v140
	v_or_b32_e32 v114, v141, v114
	v_cvt_f32_u32_e32 v149, v114
	v_sub_u32_e32 v148, 32, v148
	v_or_b32_e32 v114, 0x800, v178
	v_lshl_add_u64 v[140:141], v[178:179], 1, s[8:9]
	v_ldexp_f32 v148, v149, v148
	v_fmamk_f32 v150, v148, 0x2d800000, v1
	v_div_scale_f32 v151, s[0:1], v150, v150, 1.0
	v_rcp_f32_e32 v152, v151
	v_lshl_add_u64 v[148:149], v[114:115], 1, s[8:9]
	v_div_scale_f32 v114, vcc, 1.0, v150, 1.0
	v_fma_f32 v115, -v151, v152, 1.0
	v_fmac_f32_e32 v152, v115, v152
	v_mul_f32_e32 v115, v114, v152
	v_fma_f32 v153, -v151, v115, v114
	v_fmac_f32_e32 v115, v153, v152
	v_fma_f32 v114, -v151, v115, v114
	v_div_fmas_f32 v114, v114, v152, v115
	v_div_fixup_f32 v114, v114, v150, 1.0
	v_pk_mul_f32 v[116:117], v[116:117], v[114:115] op_sel_hi:[1,0]
	v_pk_mul_f32 v[118:119], v[118:119], v[114:115] op_sel_hi:[1,0]
	v_pk_mul_f32 v[120:121], v[120:121], v[114:115] op_sel_hi:[1,0]
	v_pk_mul_f32 v[122:123], v[122:123], v[114:115] op_sel_hi:[1,0]
	v_pk_mul_f32 v[124:125], v[124:125], v[114:115] op_sel_hi:[1,0]
	v_pk_mul_f32 v[126:127], v[126:127], v[114:115] op_sel_hi:[1,0]
	v_pk_mul_f32 v[128:129], v[128:129], v[114:115] op_sel_hi:[1,0]
	v_pk_mul_f32 v[146:147], v[146:147], v[114:115] op_sel_hi:[1,0]
	v_cvt_pk_bf16_f32 v114, v118, v119
	v_cvt_pk_bf16_f32 v115, v116, v117
	v_cvt_pk_bf16_f32 v116, v122, v123
	v_cvt_pk_bf16_f32 v117, v120, v121
	v_cvt_pk_bf16_f32 v118, v126, v127
	v_cvt_pk_bf16_f32 v119, v124, v125
	v_cvt_pk_bf16_f32 v120, v146, v147
	v_cvt_pk_bf16_f32 v121, v128, v129
	global_store_dwordx4 v[140:141], v[114:117], off
	global_store_dwordx4 v[148:149], v[118:121], off
	s_nop 1
	v_max_f32_e32 v122, v100, v100
	v_max_f32_e32 v118, v104, v104
	v_max_f32_e32 v120, v102, v102
	v_max_f32_e32 v102, 0, v110
	v_max_f32_e32 v110, 0, v118
	v_max_f32_e32 v118, 0, v98
	v_max_f32_e32 v100, 0, v112
	v_max_f32_e32 v112, 0, v120
	v_max_f32_e32 v117, v105, v105
	v_max_f32_e32 v121, v101, v101
	v_max_f32_e32 v116, v107, v107
	v_max_f32_e32 v119, v103, v103
	v_max_f32_e32 v103, 0, v111
	v_max_f32_e32 v111, 0, v117
	v_max_f32_e32 v117, 0, v121
	v_max_f32_e32 v105, 0, v109
	v_max_f32_e32 v109, 0, v116
	v_max_f32_e32 v116, 0, v122
	v_max_f32_e32 v123, v99, v99
	v_mov_b32_e32 v99, v179
	v_max_f32_e32 v101, 0, v113
	v_max_f32_e32 v113, 0, v119
	v_max_f32_e32 v119, 0, v123
	v_max_f32_e32 v104, 0, v108
	v_max_f32_e32 v108, 0, v106
; __device__ __forceinline__ u32x4 pack8(const f32x4& a, const f32x4& b) { u32x4 w; w.x = cvt_pk_bf16(a[0], a[1]); w.y = cvt_pk_bf16(a[2], a[3]); w.z = cvt_pk_bf16(b[0], b[1]); w.w = cvt_pk_bf16(b[2], b[3]); return w; }
;     __device__ __forceinline__ void operator()(const f32x4 (&acc)[2][2][4][2], const Unit& u, int wr, int wc, int fr, int fq) const {
;     ...
;             for (int m = 0; m < 4; ++m) { const float r2 = 1.f / ((float)ss[row0 + ai * HALF + m * 16] * (SS_INV / DM) + 1e-6f);
; #pragma unroll
;                 for (int bj = 0; bj < 2; ++bj) { f32x4 v0 = acc[ai][bj][m][0], v1 = acc[ai][bj][m][1];
;                     v0 = __builtin_elementwise_max(v0, (f32x4){0.f, 0.f, 0.f, 0.f}); v1 = __builtin_elementwise_max(v1, (f32x4){0.f, 0.f, 0.f, 0.f}); v0 = v0 * v0 * r2; v1 = v1 * v1 * r2;
;                     *(u32x4*)(O + (size_t)(base + (unsigned)(8 * ai + m) * kb + (unsigned)(4 * bj) * 512u)) = pack8(v0, v1); } }
	v_pk_mul_f32 v[102:103], v[102:103], v[102:103]
	v_pk_mul_f32 v[100:101], v[100:101], v[100:101]
	v_pk_mul_f32 v[108:109], v[108:109], v[108:109]
	v_pk_mul_f32 v[104:105], v[104:105], v[104:105]
	v_mov_b32_e32 v107, v179
	v_pk_mul_f32 v[112:113], v[112:113], v[112:113]
	v_pk_mul_f32 v[110:111], v[110:111], v[110:111]
	v_pk_mul_f32 v[118:119], v[118:119], v[118:119]
	v_pk_mul_f32 v[116:117], v[116:117], v[116:117]
	v_add_u32_e32 v106, 0x40000, v178
	v_lshl_add_u64 v[106:107], v[106:107], 1, s[8:9]
	v_max_f32_e32 v34, v34, v34
	v_max_f32_e32 v48, v48, v48
	v_max_f32_e32 v47, v47, v47
	v_max_f32_e32 v45, v45, v45
	v_max_f32_e32 v49, v49, v49
	v_max_f32_e32 v44, v44, v44
	v_max_f32_e32 v42, v42, v42
	v_max_f32_e32 v30, v30, v30
	v_max_f32_e32 v18, v18, v18
	v_max_f32_e32 v32, v32, v32
	v_max_f32_e32 v31, v31, v31
	v_max_f32_e32 v29, v29, v29
	v_max_f32_e32 v33, v33, v33
	v_max_f32_e32 v28, v28, v28
	v_max_f32_e32 v26, v26, v26
	v_max_f32_e32 v12, v12, v12
	v_max_f32_e32 v15, v15, v15
	v_max_f32_e32 v14, v14, v14
	v_max_f32_e32 v16, v16, v16
	v_max_f32_e32 v17, v17, v17
	v_max_f32_e32 v13, v13, v13
	v_max_f32_e32 v10, v10, v10
	v_mov_b32_e32 v114, v162
	v_mov_b32_e32 v115, v163
	v_ffbh_u32_e32 v98, v115
	v_min_u32_e32 v120, 32, v98
	v_lshlrev_b64 v[114:115], v120, v[114:115]
	v_min_u32_e32 v98, 1, v114
	v_or_b32_e32 v98, v115, v98
	v_cvt_f32_u32_e32 v114, v98
	v_sub_u32_e32 v115, 32, v120
	v_add_u32_e32 v98, 0x40800, v178
	v_ldexp_f32 v114, v114, v115
	v_fmamk_f32 v120, v114, 0x2d800000, v1
	v_div_scale_f32 v121, s[0:1], v120, v120, 1.0
	v_rcp_f32_e32 v122, v121
	v_lshl_add_u64 v[114:115], v[98:99], 1, s[8:9]
	v_div_scale_f32 v98, vcc, 1.0, v120, 1.0
	v_fma_f32 v99, -v121, v122, 1.0
	v_fmac_f32_e32 v122, v99, v122
	v_mul_f32_e32 v99, v98, v122
	v_fma_f32 v123, -v121, v99, v98
	v_fmac_f32_e32 v99, v123, v122
	v_fma_f32 v98, -v121, v99, v98
	v_div_fmas_f32 v98, v98, v122, v99
	v_div_fixup_f32 v98, v98, v120, 1.0
	v_pk_mul_f32 v[100:101], v[100:101], v[98:99] op_sel_hi:[1,0]
	v_pk_mul_f32 v[102:103], v[102:103], v[98:99] op_sel_hi:[1,0]
	v_pk_mul_f32 v[104:105], v[104:105], v[98:99] op_sel_hi:[1,0]
	v_pk_mul_f32 v[108:109], v[108:109], v[98:99] op_sel_hi:[1,0]
	v_pk_mul_f32 v[110:111], v[110:111], v[98:99] op_sel_hi:[1,0]
	v_pk_mul_f32 v[112:113], v[112:113], v[98:99] op_sel_hi:[1,0]
	v_pk_mul_f32 v[116:117], v[116:117], v[98:99] op_sel_hi:[1,0]
	v_pk_mul_f32 v[118:119], v[118:119], v[98:99] op_sel_hi:[1,0]
	v_cvt_pk_bf16_f32 v98, v102, v103
	v_cvt_pk_bf16_f32 v99, v100, v101
	v_cvt_pk_bf16_f32 v100, v108, v109
	v_cvt_pk_bf16_f32 v101, v104, v105
	v_cvt_pk_bf16_f32 v102, v112, v113
	v_cvt_pk_bf16_f32 v103, v110, v111
	v_cvt_pk_bf16_f32 v104, v118, v119
	v_cvt_pk_bf16_f32 v105, v116, v117
	global_store_dwordx4 v[106:107], v[98:101], off
	global_store_dwordx4 v[114:115], v[102:105], off
	s_nop 1
	v_max_f32_e32 v106, v84, v84
	v_max_f32_e32 v102, v88, v88
	v_max_f32_e32 v104, v86, v86
	v_max_f32_e32 v86, 0, v94
	v_max_f32_e32 v94, 0, v102
	v_max_f32_e32 v102, 0, v82
	v_max_f32_e32 v84, 0, v96
	v_max_f32_e32 v96, 0, v104
	v_max_f32_e32 v101, v89, v89
	v_max_f32_e32 v105, v85, v85
	v_max_f32_e32 v100, v91, v91
	v_max_f32_e32 v103, v87, v87
	v_max_f32_e32 v87, 0, v95
	v_max_f32_e32 v95, 0, v101
	v_max_f32_e32 v101, 0, v105
	v_max_f32_e32 v89, 0, v93
	v_max_f32_e32 v93, 0, v100
	v_max_f32_e32 v100, 0, v106
	v_max_f32_e32 v107, v83, v83
	v_mov_b32_e32 v83, v179
	v_max_f32_e32 v85, 0, v97
	v_max_f32_e32 v97, 0, v103
	v_max_f32_e32 v103, 0, v107
	v_max_f32_e32 v88, 0, v92
	v_max_f32_e32 v92, 0, v90
	v_pk_mul_f32 v[86:87], v[86:87], v[86:87]
	v_pk_mul_f32 v[84:85], v[84:85], v[84:85]
	v_pk_mul_f32 v[92:93], v[92:93], v[92:93]
	v_pk_mul_f32 v[88:89], v[88:89], v[88:89]
	v_mov_b32_e32 v91, v179
	v_pk_mul_f32 v[96:97], v[96:97], v[96:97]
	v_pk_mul_f32 v[94:95], v[94:95], v[94:95]
	v_pk_mul_f32 v[102:103], v[102:103], v[102:103]
	v_pk_mul_f32 v[100:101], v[100:101], v[100:101]
	v_add_u32_e32 v90, 0x80000, v178
	v_lshl_add_u64 v[90:91], v[90:91], 1, s[8:9]
	v_mov_b32_e32 v98, v164
	v_mov_b32_e32 v99, v165
	v_ffbh_u32_e32 v82, v99
	v_min_u32_e32 v104, 32, v82
	v_lshlrev_b64 v[98:99], v104, v[98:99]
	v_min_u32_e32 v82, 1, v98
	v_or_b32_e32 v82, v99, v82
	v_cvt_f32_u32_e32 v98, v82
	v_sub_u32_e32 v99, 32, v104
	v_add_u32_e32 v82, 0x80800, v178
	v_ldexp_f32 v98, v98, v99
	v_fmamk_f32 v104, v98, 0x2d800000, v1
	v_div_scale_f32 v105, s[0:1], v104, v104, 1.0
	v_rcp_f32_e32 v106, v105
	v_lshl_add_u64 v[98:99], v[82:83], 1, s[8:9]
	v_div_scale_f32 v82, vcc, 1.0, v104, 1.0
	v_fma_f32 v83, -v105, v106, 1.0
	v_fmac_f32_e32 v106, v83, v106
	v_mul_f32_e32 v83, v82, v106
	v_fma_f32 v107, -v105, v83, v82
	v_fmac_f32_e32 v83, v107, v106
	v_fma_f32 v82, -v105, v83, v82
	v_div_fmas_f32 v82, v82, v106, v83
	v_div_fixup_f32 v82, v82, v104, 1.0
	v_pk_mul_f32 v[84:85], v[84:85], v[82:83] op_sel_hi:[1,0]
	v_pk_mul_f32 v[86:87], v[86:87], v[82:83] op_sel_hi:[1,0]
	v_pk_mul_f32 v[88:89], v[88:89], v[82:83] op_sel_hi:[1,0]
	v_pk_mul_f32 v[92:93], v[92:93], v[82:83] op_sel_hi:[1,0]
	v_pk_mul_f32 v[94:95], v[94:95], v[82:83] op_sel_hi:[1,0]
	v_pk_mul_f32 v[96:97], v[96:97], v[82:83] op_sel_hi:[1,0]
	v_pk_mul_f32 v[100:101], v[100:101], v[82:83] op_sel_hi:[1,0]
	v_pk_mul_f32 v[102:103], v[102:103], v[82:83] op_sel_hi:[1,0]
	v_cvt_pk_bf16_f32 v82, v86, v87
	v_cvt_pk_bf16_f32 v83, v84, v85
	v_cvt_pk_bf16_f32 v84, v92, v93
	v_cvt_pk_bf16_f32 v85, v88, v89
	v_cvt_pk_bf16_f32 v86, v96, v97
	v_cvt_pk_bf16_f32 v87, v94, v95
	v_cvt_pk_bf16_f32 v88, v102, v103
	v_cvt_pk_bf16_f32 v89, v100, v101
	global_store_dwordx4 v[90:91], v[82:85], off
	global_store_dwordx4 v[98:99], v[86:89], off
	s_nop 1
; __device__ __forceinline__ u32x4 pack8(const f32x4& a, const f32x4& b) { u32x4 w; w.x = cvt_pk_bf16(a[0], a[1]); w.y = cvt_pk_bf16(a[2], a[3]); w.z = cvt_pk_bf16(b[0], b[1]); w.w = cvt_pk_bf16(b[2], b[3]); return w; }
;     __device__ __forceinline__ void operator()(const f32x4 (&acc)[2][2][4][2], const Unit& u, int wr, int wc, int fr, int fq) const {
;     ...
;             for (int m = 0; m < 4; ++m) { const float r2 = 1.f / ((float)ss[row0 + ai * HALF + m * 16] * (SS_INV / DM) + 1e-6f);
; #pragma unroll
;                 for (int bj = 0; bj < 2; ++bj) { f32x4 v0 = acc[ai][bj][m][0], v1 = acc[ai][bj][m][1];
;                     v0 = __builtin_elementwise_max(v0, (f32x4){0.f, 0.f, 0.f, 0.f}); v1 = __builtin_elementwise_max(v1, (f32x4){0.f, 0.f, 0.f, 0.f}); v0 = v0 * v0 * r2; v1 = v1 * v1 * r2;
;                     *(u32x4*)(O + (size_t)(base + (unsigned)(8 * ai + m) * kb + (unsigned)(4 * bj) * 512u)) = pack8(v0, v1); } }
	v_max_f32_e32 v90, v68, v68
	v_max_f32_e32 v86, v72, v72
	v_max_f32_e32 v88, v70, v70
	v_max_f32_e32 v70, 0, v78
	v_max_f32_e32 v78, 0, v86
	v_max_f32_e32 v86, 0, v66
	v_max_f32_e32 v68, 0, v80
	v_max_f32_e32 v80, 0, v88
	v_max_f32_e32 v85, v73, v73
	v_max_f32_e32 v89, v69, v69
	v_max_f32_e32 v84, v75, v75
	v_max_f32_e32 v87, v71, v71
	v_max_f32_e32 v71, 0, v79
	v_max_f32_e32 v79, 0, v85
	v_max_f32_e32 v85, 0, v89
	v_max_f32_e32 v73, 0, v77
	v_max_f32_e32 v77, 0, v84
	v_max_f32_e32 v84, 0, v90
	v_max_f32_e32 v91, v67, v67
	v_mov_b32_e32 v67, v179
	v_max_f32_e32 v69, 0, v81
	v_max_f32_e32 v81, 0, v87
	v_max_f32_e32 v87, 0, v91
	v_max_f32_e32 v72, 0, v76
	v_max_f32_e32 v76, 0, v74
	v_pk_mul_f32 v[70:71], v[70:71], v[70:71]
	v_pk_mul_f32 v[68:69], v[68:69], v[68:69]
	v_pk_mul_f32 v[76:77], v[76:77], v[76:77]
	v_pk_mul_f32 v[72:73], v[72:73], v[72:73]
	v_mov_b32_e32 v75, v179
	v_pk_mul_f32 v[80:81], v[80:81], v[80:81]
	v_pk_mul_f32 v[78:79], v[78:79], v[78:79]
	v_pk_mul_f32 v[86:87], v[86:87], v[86:87]
	v_pk_mul_f32 v[84:85], v[84:85], v[84:85]
	v_add_u32_e32 v74, 0xc0000, v178
	v_lshl_add_u64 v[74:75], v[74:75], 1, s[8:9]
	v_mov_b32_e32 v82, v166
	v_mov_b32_e32 v83, v167
	v_ffbh_u32_e32 v66, v83
	v_min_u32_e32 v88, 32, v66
	v_lshlrev_b64 v[82:83], v88, v[82:83]
	v_min_u32_e32 v66, 1, v82
	v_or_b32_e32 v66, v83, v66
	v_cvt_f32_u32_e32 v82, v66
	v_sub_u32_e32 v83, 32, v88
	v_add_u32_e32 v66, 0xc0800, v178
	v_ldexp_f32 v82, v82, v83
	v_fmamk_f32 v88, v82, 0x2d800000, v1
	v_div_scale_f32 v89, s[0:1], v88, v88, 1.0
	v_rcp_f32_e32 v90, v89
	v_lshl_add_u64 v[82:83], v[66:67], 1, s[8:9]
	v_div_scale_f32 v66, vcc, 1.0, v88, 1.0
	v_fma_f32 v67, -v89, v90, 1.0
	v_fmac_f32_e32 v90, v67, v90
	v_mul_f32_e32 v67, v66, v90
	v_fma_f32 v91, -v89, v67, v66
	v_fmac_f32_e32 v67, v91, v90
	v_fma_f32 v66, -v89, v67, v66
	v_div_fmas_f32 v66, v66, v90, v67
	v_div_fixup_f32 v66, v66, v88, 1.0
	v_pk_mul_f32 v[68:69], v[68:69], v[66:67] op_sel_hi:[1,0]
	v_pk_mul_f32 v[70:71], v[70:71], v[66:67] op_sel_hi:[1,0]
	v_pk_mul_f32 v[72:73], v[72:73], v[66:67] op_sel_hi:[1,0]
	v_pk_mul_f32 v[76:77], v[76:77], v[66:67] op_sel_hi:[1,0]
	v_pk_mul_f32 v[78:79], v[78:79], v[66:67] op_sel_hi:[1,0]
	v_pk_mul_f32 v[80:81], v[80:81], v[66:67] op_sel_hi:[1,0]
	v_pk_mul_f32 v[84:85], v[84:85], v[66:67] op_sel_hi:[1,0]
	v_pk_mul_f32 v[86:87], v[86:87], v[66:67] op_sel_hi:[1,0]
	v_cvt_pk_bf16_f32 v66, v70, v71
	v_cvt_pk_bf16_f32 v67, v68, v69
	v_cvt_pk_bf16_f32 v68, v76, v77
	v_cvt_pk_bf16_f32 v69, v72, v73
	v_cvt_pk_bf16_f32 v70, v80, v81
	v_cvt_pk_bf16_f32 v71, v78, v79
	v_cvt_pk_bf16_f32 v72, v86, v87
	v_cvt_pk_bf16_f32 v73, v84, v85
	global_store_dwordx4 v[74:75], v[66:69], off
	global_store_dwordx4 v[82:83], v[70:73], off
	s_nop 1
	v_max_f32_e32 v74, v52, v52
	v_max_f32_e32 v70, v56, v56
	v_max_f32_e32 v72, v54, v54
	v_max_f32_e32 v54, 0, v62
	v_max_f32_e32 v62, 0, v70
	v_max_f32_e32 v70, 0, v50
	v_max_f32_e32 v52, 0, v64
	v_max_f32_e32 v64, 0, v72
	v_max_f32_e32 v69, v57, v57
	v_max_f32_e32 v73, v53, v53
	v_max_f32_e32 v68, v59, v59
	v_max_f32_e32 v71, v55, v55
	v_max_f32_e32 v55, 0, v63
	v_max_f32_e32 v63, 0, v69
	v_max_f32_e32 v69, 0, v73
	v_max_f32_e32 v57, 0, v61
	v_max_f32_e32 v61, 0, v68
	v_max_f32_e32 v68, 0, v74
	v_max_f32_e32 v75, v51, v51
	v_mov_b32_e32 v51, v179
	v_max_f32_e32 v53, 0, v65
	v_max_f32_e32 v65, 0, v71
	v_max_f32_e32 v71, 0, v75
	v_max_f32_e32 v56, 0, v60
	v_max_f32_e32 v60, 0, v58
	v_pk_mul_f32 v[54:55], v[54:55], v[54:55]
	v_pk_mul_f32 v[52:53], v[52:53], v[52:53]
	v_pk_mul_f32 v[60:61], v[60:61], v[60:61]
	v_pk_mul_f32 v[56:57], v[56:57], v[56:57]
	v_mov_b32_e32 v59, v179
	v_pk_mul_f32 v[64:65], v[64:65], v[64:65]
	v_pk_mul_f32 v[62:63], v[62:63], v[62:63]
	v_pk_mul_f32 v[70:71], v[70:71], v[70:71]
	v_pk_mul_f32 v[68:69], v[68:69], v[68:69]
	v_add_u32_e32 v58, 0x200000, v178
	v_lshl_add_u64 v[58:59], v[58:59], 1, s[8:9]
	v_mov_b32_e32 v66, v168
	v_mov_b32_e32 v67, v169
	v_ffbh_u32_e32 v50, v67
	v_min_u32_e32 v72, 32, v50
	v_lshlrev_b64 v[66:67], v72, v[66:67]
	v_min_u32_e32 v50, 1, v66
	v_or_b32_e32 v50, v67, v50
	v_cvt_f32_u32_e32 v66, v50
	v_sub_u32_e32 v67, 32, v72
	v_add_u32_e32 v50, 0x200800, v178
	v_ldexp_f32 v66, v66, v67
	v_fmamk_f32 v72, v66, 0x2d800000, v1
	v_div_scale_f32 v73, s[0:1], v72, v72, 1.0
	v_rcp_f32_e32 v74, v73
	v_lshl_add_u64 v[66:67], v[50:51], 1, s[8:9]
	v_div_scale_f32 v50, vcc, 1.0, v72, 1.0
	v_fma_f32 v51, -v73, v74, 1.0
	v_fmac_f32_e32 v74, v51, v74
	v_mul_f32_e32 v51, v50, v74
	v_fma_f32 v75, -v73, v51, v50
	v_fmac_f32_e32 v51, v75, v74
	v_fma_f32 v50, -v73, v51, v50
	v_div_fmas_f32 v50, v50, v74, v51
	v_div_fixup_f32 v50, v50, v72, 1.0
	v_pk_mul_f32 v[52:53], v[52:53], v[50:51] op_sel_hi:[1,0]
	v_pk_mul_f32 v[54:55], v[54:55], v[50:51] op_sel_hi:[1,0]
	v_pk_mul_f32 v[56:57], v[56:57], v[50:51] op_sel_hi:[1,0]
	v_pk_mul_f32 v[60:61], v[60:61], v[50:51] op_sel_hi:[1,0]
	v_pk_mul_f32 v[62:63], v[62:63], v[50:51] op_sel_hi:[1,0]
	v_pk_mul_f32 v[64:65], v[64:65], v[50:51] op_sel_hi:[1,0]
	v_pk_mul_f32 v[68:69], v[68:69], v[50:51] op_sel_hi:[1,0]
	v_pk_mul_f32 v[70:71], v[70:71], v[50:51] op_sel_hi:[1,0]
	v_cvt_pk_bf16_f32 v50, v54, v55
	v_cvt_pk_bf16_f32 v51, v52, v53
	v_cvt_pk_bf16_f32 v52, v60, v61
	v_cvt_pk_bf16_f32 v53, v56, v57
	v_cvt_pk_bf16_f32 v54, v64, v65
	v_cvt_pk_bf16_f32 v55, v62, v63
	v_cvt_pk_bf16_f32 v56, v70, v71
	v_cvt_pk_bf16_f32 v57, v68, v69
	global_store_dwordx4 v[58:59], v[50:53], off
	global_store_dwordx4 v[66:67], v[54:57], off
	s_nop 1
	v_max_f32_e32 v58, v36, v36
	v_max_f32_e32 v54, v40, v40
	v_max_f32_e32 v56, v38, v38
	v_max_f32_e32 v38, 0, v46
	v_max_f32_e32 v46, 0, v54
	v_max_f32_e32 v54, 0, v34
; __device__ __forceinline__ u32x4 pack8(const f32x4& a, const f32x4& b) { u32x4 w; w.x = cvt_pk_bf16(a[0], a[1]); w.y = cvt_pk_bf16(a[2], a[3]); w.z = cvt_pk_bf16(b[0], b[1]); w.w = cvt_pk_bf16(b[2], b[3]); return w; }
;     __device__ __forceinline__ void operator()(const f32x4 (&acc)[2][2][4][2], const Unit& u, int wr, int wc, int fr, int fq) const {
;     ...
;             for (int m = 0; m < 4; ++m) { const float r2 = 1.f / ((float)ss[row0 + ai * HALF + m * 16] * (SS_INV / DM) + 1e-6f);
; #pragma unroll
;                 for (int bj = 0; bj < 2; ++bj) { f32x4 v0 = acc[ai][bj][m][0], v1 = acc[ai][bj][m][1];
;                     v0 = __builtin_elementwise_max(v0, (f32x4){0.f, 0.f, 0.f, 0.f}); v1 = __builtin_elementwise_max(v1, (f32x4){0.f, 0.f, 0.f, 0.f}); v0 = v0 * v0 * r2; v1 = v1 * v1 * r2;
;                     *(u32x4*)(O + (size_t)(base + (unsigned)(8 * ai + m) * kb + (unsigned)(4 * bj) * 512u)) = pack8(v0, v1); } }
	v_max_f32_e32 v36, 0, v48
	v_max_f32_e32 v48, 0, v56
	v_max_f32_e32 v53, v41, v41
	v_max_f32_e32 v57, v37, v37
	v_max_f32_e32 v52, v43, v43
	v_max_f32_e32 v55, v39, v39
	v_max_f32_e32 v39, 0, v47
	v_max_f32_e32 v47, 0, v53
	v_max_f32_e32 v53, 0, v57
	v_max_f32_e32 v41, 0, v45
	v_max_f32_e32 v45, 0, v52
	v_max_f32_e32 v52, 0, v58
	v_max_f32_e32 v59, v35, v35
	v_mov_b32_e32 v35, v179
	v_max_f32_e32 v37, 0, v49
	v_max_f32_e32 v49, 0, v55
	v_max_f32_e32 v55, 0, v59
	v_max_f32_e32 v40, 0, v44
	v_max_f32_e32 v44, 0, v42
	v_pk_mul_f32 v[38:39], v[38:39], v[38:39]
	v_pk_mul_f32 v[36:37], v[36:37], v[36:37]
	v_pk_mul_f32 v[44:45], v[44:45], v[44:45]
	v_pk_mul_f32 v[40:41], v[40:41], v[40:41]
	v_mov_b32_e32 v43, v179
	v_pk_mul_f32 v[48:49], v[48:49], v[48:49]
	v_pk_mul_f32 v[46:47], v[46:47], v[46:47]
	v_pk_mul_f32 v[54:55], v[54:55], v[54:55]
	v_pk_mul_f32 v[52:53], v[52:53], v[52:53]
	v_add_u32_e32 v42, 0x240000, v178
	v_lshl_add_u64 v[42:43], v[42:43], 1, s[8:9]
	v_mov_b32_e32 v50, v170
	v_mov_b32_e32 v51, v171
	v_ffbh_u32_e32 v34, v51
	v_min_u32_e32 v56, 32, v34
	v_lshlrev_b64 v[50:51], v56, v[50:51]
	v_min_u32_e32 v34, 1, v50
	v_or_b32_e32 v34, v51, v34
	v_cvt_f32_u32_e32 v50, v34
	v_sub_u32_e32 v51, 32, v56
	v_add_u32_e32 v34, 0x240800, v178
	v_ldexp_f32 v50, v50, v51
	v_fmamk_f32 v56, v50, 0x2d800000, v1
	v_div_scale_f32 v57, s[0:1], v56, v56, 1.0
	v_rcp_f32_e32 v58, v57
	v_lshl_add_u64 v[50:51], v[34:35], 1, s[8:9]
	v_div_scale_f32 v34, vcc, 1.0, v56, 1.0
	v_fma_f32 v35, -v57, v58, 1.0
	v_fmac_f32_e32 v58, v35, v58
	v_mul_f32_e32 v35, v34, v58
	v_fma_f32 v59, -v57, v35, v34
	v_fmac_f32_e32 v35, v59, v58
	v_fma_f32 v34, -v57, v35, v34
	v_div_fmas_f32 v34, v34, v58, v35
	v_div_fixup_f32 v34, v34, v56, 1.0
	v_pk_mul_f32 v[36:37], v[36:37], v[34:35] op_sel_hi:[1,0]
	v_pk_mul_f32 v[38:39], v[38:39], v[34:35] op_sel_hi:[1,0]
	v_pk_mul_f32 v[40:41], v[40:41], v[34:35] op_sel_hi:[1,0]
	v_pk_mul_f32 v[44:45], v[44:45], v[34:35] op_sel_hi:[1,0]
	v_pk_mul_f32 v[46:47], v[46:47], v[34:35] op_sel_hi:[1,0]
	v_pk_mul_f32 v[48:49], v[48:49], v[34:35] op_sel_hi:[1,0]
	v_pk_mul_f32 v[52:53], v[52:53], v[34:35] op_sel_hi:[1,0]
	v_pk_mul_f32 v[54:55], v[54:55], v[34:35] op_sel_hi:[1,0]
	v_cvt_pk_bf16_f32 v34, v38, v39
	v_cvt_pk_bf16_f32 v35, v36, v37
	v_cvt_pk_bf16_f32 v36, v44, v45
	v_cvt_pk_bf16_f32 v37, v40, v41
	v_cvt_pk_bf16_f32 v38, v48, v49
	v_cvt_pk_bf16_f32 v39, v46, v47
	v_cvt_pk_bf16_f32 v40, v54, v55
	v_cvt_pk_bf16_f32 v41, v52, v53
	global_store_dwordx4 v[42:43], v[34:37], off
	global_store_dwordx4 v[50:51], v[38:41], off
	s_nop 1
	v_max_f32_e32 v42, v20, v20
	v_max_f32_e32 v38, v24, v24
	v_max_f32_e32 v40, v22, v22
	v_max_f32_e32 v22, 0, v30
	v_max_f32_e32 v30, 0, v38
	v_max_f32_e32 v38, 0, v18
	v_max_f32_e32 v20, 0, v32
	v_max_f32_e32 v32, 0, v40
	v_max_f32_e32 v37, v25, v25
	v_max_f32_e32 v41, v21, v21
	v_max_f32_e32 v36, v27, v27
	v_max_f32_e32 v39, v23, v23
	v_max_f32_e32 v23, 0, v31
	v_max_f32_e32 v31, 0, v37
	v_max_f32_e32 v37, 0, v41
	v_max_f32_e32 v25, 0, v29
	v_max_f32_e32 v29, 0, v36
	v_max_f32_e32 v36, 0, v42
	v_max_f32_e32 v43, v19, v19
	v_mov_b32_e32 v19, v179
	v_max_f32_e32 v21, 0, v33
	v_max_f32_e32 v33, 0, v39
	v_max_f32_e32 v39, 0, v43
	v_max_f32_e32 v24, 0, v28
	v_max_f32_e32 v28, 0, v26
	v_pk_mul_f32 v[22:23], v[22:23], v[22:23]
	v_pk_mul_f32 v[20:21], v[20:21], v[20:21]
	v_pk_mul_f32 v[28:29], v[28:29], v[28:29]
	v_pk_mul_f32 v[24:25], v[24:25], v[24:25]
	v_mov_b32_e32 v27, v179
	v_pk_mul_f32 v[32:33], v[32:33], v[32:33]
	v_pk_mul_f32 v[30:31], v[30:31], v[30:31]
	v_pk_mul_f32 v[38:39], v[38:39], v[38:39]
	v_pk_mul_f32 v[36:37], v[36:37], v[36:37]
	v_add_u32_e32 v26, 0x280000, v178
	v_lshl_add_u64 v[26:27], v[26:27], 1, s[8:9]
	v_mov_b32_e32 v34, v172
	v_mov_b32_e32 v35, v173
	v_ffbh_u32_e32 v18, v35
	v_min_u32_e32 v40, 32, v18
	v_lshlrev_b64 v[34:35], v40, v[34:35]
	v_min_u32_e32 v18, 1, v34
	v_or_b32_e32 v18, v35, v18
	v_cvt_f32_u32_e32 v34, v18
	v_sub_u32_e32 v35, 32, v40
	v_add_u32_e32 v18, 0x280800, v178
	v_ldexp_f32 v34, v34, v35
	v_fmamk_f32 v40, v34, 0x2d800000, v1
; __device__ __forceinline__ u32x4 pack8(const f32x4& a, const f32x4& b) { u32x4 w; w.x = cvt_pk_bf16(a[0], a[1]); w.y = cvt_pk_bf16(a[2], a[3]); w.z = cvt_pk_bf16(b[0], b[1]); w.w = cvt_pk_bf16(b[2], b[3]); return w; }
; #define PG8_BAR __builtin_amdgcn_s_barrier()
;     __device__ __forceinline__ void operator()(const f32x4 (&acc)[2][2][4][2], const Unit& u, int wr, int wc, int fr, int fq) const {
;     ...
;             for (int m = 0; m < 4; ++m) { const float r2 = 1.f / ((float)ss[row0 + ai * HALF + m * 16] * (SS_INV / DM) + 1e-6f);
; #pragma unroll
;                 for (int bj = 0; bj < 2; ++bj) { f32x4 v0 = acc[ai][bj][m][0], v1 = acc[ai][bj][m][1];
;                     v0 = __builtin_elementwise_max(v0, (f32x4){0.f, 0.f, 0.f, 0.f}); v1 = __builtin_elementwise_max(v1, (f32x4){0.f, 0.f, 0.f, 0.f}); v0 = v0 * v0 * r2; v1 = v1 * v1 * r2;
;                     *(u32x4*)(O + (size_t)(base + (unsigned)(8 * ai + m) * kb + (unsigned)(4 * bj) * 512u)) = pack8(v0, v1); } }
; template <class Epi, class Sched, bool ALIGN_EPI, int LMASK = -1, int LMASKB = LMASK>
; __device__ __forceinline__ void gemm_phase(PG8_LAS unsigned char* lds, const Gemm g, const Sched& S, const Epi& E) {
;     ...
;         if (!has_next) break;
; #pragma unroll
;         for (int a = 0; a < 2; ++a)
; #pragma unroll
;             for (int b = 0; b < 2; ++b)
; #pragma unroll
;                 for (int m = 0; m < 4; ++m)
; #pragma unroll
;                     for (int n = 0; n < 2; ++n) acc[a][b][m][n] = (f32x4){0.f, 0.f, 0.f, 0.f};
;         cur = nxt; cA = nA; cB = nB; ++ui;
;         if constexpr (ALIGN_EPI) { if (wr == 1) PG8_BAR; }
	v_div_scale_f32 v41, s[0:1], v40, v40, 1.0
	v_rcp_f32_e32 v42, v41
	v_lshl_add_u64 v[34:35], v[18:19], 1, s[8:9]
	v_div_scale_f32 v18, vcc, 1.0, v40, 1.0
	v_fma_f32 v19, -v41, v42, 1.0
	v_fmac_f32_e32 v42, v19, v42
	v_mul_f32_e32 v19, v18, v42
	v_fma_f32 v43, -v41, v19, v18
	v_fmac_f32_e32 v19, v43, v42
	v_fma_f32 v18, -v41, v19, v18
	v_div_fmas_f32 v18, v18, v42, v19
	v_div_fixup_f32 v18, v18, v40, 1.0
	v_pk_mul_f32 v[20:21], v[20:21], v[18:19] op_sel_hi:[1,0]
	v_pk_mul_f32 v[22:23], v[22:23], v[18:19] op_sel_hi:[1,0]
	v_pk_mul_f32 v[24:25], v[24:25], v[18:19] op_sel_hi:[1,0]
	v_pk_mul_f32 v[28:29], v[28:29], v[18:19] op_sel_hi:[1,0]
	v_pk_mul_f32 v[30:31], v[30:31], v[18:19] op_sel_hi:[1,0]
	v_pk_mul_f32 v[32:33], v[32:33], v[18:19] op_sel_hi:[1,0]
	v_pk_mul_f32 v[36:37], v[36:37], v[18:19] op_sel_hi:[1,0]
	v_pk_mul_f32 v[38:39], v[38:39], v[18:19] op_sel_hi:[1,0]
	v_cvt_pk_bf16_f32 v18, v22, v23
	v_cvt_pk_bf16_f32 v19, v20, v21
	v_cvt_pk_bf16_f32 v20, v28, v29
	v_cvt_pk_bf16_f32 v21, v24, v25
	v_cvt_pk_bf16_f32 v22, v32, v33
	v_cvt_pk_bf16_f32 v23, v30, v31
	v_cvt_pk_bf16_f32 v24, v38, v39
	v_cvt_pk_bf16_f32 v25, v36, v37
	global_store_dwordx4 v[26:27], v[18:21], off
	global_store_dwordx4 v[34:35], v[22:25], off
	s_nop 1
	v_max_f32_e32 v26, v4, v4
	v_max_f32_e32 v22, v8, v8
	v_max_f32_e32 v24, v6, v6
	v_max_f32_e32 v6, 0, v12
	v_max_f32_e32 v12, 0, v22
	v_max_f32_e32 v23, v7, v7
	v_max_f32_e32 v25, v5, v5
	v_max_f32_e32 v5, 0, v15
	v_max_f32_e32 v15, 0, v23
	v_max_f32_e32 v4, 0, v14
	v_max_f32_e32 v14, 0, v24
	v_max_f32_e32 v28, v2, v2
	v_max_f32_e32 v2, 0, v16
	v_max_f32_e32 v16, 0, v26
	v_max_f32_e32 v27, v3, v3
	v_max_f32_e32 v3, 0, v17
	v_max_f32_e32 v17, 0, v25
	v_max_f32_e32 v21, v9, v9
	v_max_f32_e32 v7, 0, v13
	v_max_f32_e32 v13, 0, v21
	v_max_f32_e32 v21, 0, v27
	v_max_f32_e32 v20, v11, v11
	v_max_f32_e32 v9, 0, v20
	v_max_f32_e32 v8, 0, v10
	v_max_f32_e32 v20, 0, v28
	v_pk_mul_f32 v[4:5], v[4:5], v[4:5]
	v_pk_mul_f32 v[2:3], v[2:3], v[2:3]
	v_pk_mul_f32 v[8:9], v[8:9], v[8:9]
	v_pk_mul_f32 v[6:7], v[6:7], v[6:7]
	v_mov_b32_e32 v11, v179
	v_pk_mul_f32 v[14:15], v[14:15], v[14:15]
	v_pk_mul_f32 v[12:13], v[12:13], v[12:13]
	v_pk_mul_f32 v[20:21], v[20:21], v[20:21]
	v_pk_mul_f32 v[16:17], v[16:17], v[16:17]
	v_add_u32_e32 v10, 0x2c0000, v178
	v_add_u32_e32 v178, 0x2c0800, v178
	v_lshl_add_u64 v[10:11], v[10:11], 1, s[8:9]
	v_mov_b32_e32 v18, v174
	v_mov_b32_e32 v19, v175
	v_ffbh_u32_e32 v22, v19
	v_min_u32_e32 v22, 32, v22
	v_lshlrev_b64 v[18:19], v22, v[18:19]
	v_min_u32_e32 v18, 1, v18
	v_or_b32_e32 v18, v19, v18
	v_cvt_f32_u32_e32 v18, v18
	v_sub_u32_e32 v19, 32, v22
	v_ldexp_f32 v18, v18, v19
	v_fmamk_f32 v22, v18, 0x2d800000, v1
	v_div_scale_f32 v23, s[0:1], v22, v22, 1.0
	v_rcp_f32_e32 v24, v23
	v_div_scale_f32 v25, vcc, 1.0, v22, 1.0
	v_lshl_add_u64 v[18:19], v[178:179], 1, s[8:9]
	v_fma_f32 v26, -v23, v24, 1.0
	v_fmac_f32_e32 v24, v26, v24
	v_mul_f32_e32 v26, v25, v24
	v_fma_f32 v27, -v23, v26, v25
	v_fmac_f32_e32 v26, v27, v24
	v_fma_f32 v23, -v23, v26, v25
	v_div_fmas_f32 v23, v23, v24, v26
	v_div_fixup_f32 v22, v23, v22, 1.0
	v_pk_mul_f32 v[24:25], v[2:3], v[22:23] op_sel_hi:[1,0]
	v_pk_mul_f32 v[2:3], v[4:5], v[22:23] op_sel_hi:[1,0]
	v_pk_mul_f32 v[6:7], v[6:7], v[22:23] op_sel_hi:[1,0]
	v_pk_mul_f32 v[4:5], v[8:9], v[22:23] op_sel_hi:[1,0]
	s_andn2_b64 vcc, exec, s[4:5]
	v_pk_mul_f32 v[8:9], v[12:13], v[22:23] op_sel_hi:[1,0]
	v_pk_mul_f32 v[12:13], v[14:15], v[22:23] op_sel_hi:[1,0]
	v_pk_mul_f32 v[14:15], v[16:17], v[22:23] op_sel_hi:[1,0]
	v_pk_mul_f32 v[16:17], v[20:21], v[22:23] op_sel_hi:[1,0]
	v_cvt_pk_bf16_f32 v2, v2, v3
	v_cvt_pk_bf16_f32 v3, v24, v25
	v_cvt_pk_bf16_f32 v4, v4, v5
	v_cvt_pk_bf16_f32 v5, v6, v7
	s_mov_b64 s[4:5], -1
	v_cvt_pk_bf16_f32 v6, v12, v13
	v_cvt_pk_bf16_f32 v7, v8, v9
	v_cvt_pk_bf16_f32 v8, v16, v17
	v_cvt_pk_bf16_f32 v9, v14, v15
	global_store_dwordx4 v[10:11], v[2:5], off
	global_store_dwordx4 v[18:19], v[6:9], off
	s_cbranch_vccnz .LBB0_670
	s_andn2_b64 vcc, exec, s[6:7]
	s_cbranch_vccnz .LBB0_669
	s_barrier
	s_branch .LBB0_669
